# attention work stealing: queues visited in XOR order (sibling XCD of the same batch first) instead of +1 order
# speedup vs baseline: 1.0027x; 1.0009x over previous
.LBB0_827:
	s_xor_b32 s0, s96, s2
	s_and_b32 s97, s0, 7
	s_lshl_b32 s70, s97, 2
	v_readlane_b32 s4, v250, 0
	v_readlane_b32 s5, v250, 1
	s_add_u32 s28, s4, s70
	s_addc_u32 s29, s5, 0
	s_bfe_u32 s71, s0, 0x20001
	s_bitcmp0_b32 s0, 0
	s_cselect_b64 s[0:1], -1, 0
	v_writelane_b32 v250, s0, 18
	s_nop 1
	v_writelane_b32 v250, s1, 19
	s_branch .LBB0_831
